# layer 0: MG->WO grid barrier replaced by per-row-tile completion counters (release/acquire), WO units re-assigned so two-MG-tile workgroups take one late unit
# speedup vs baseline: 1.0014x; 1.0014x over previous
_Z10fwd_kernel4Args:
	s_load_dwordx2 s[86:87], s[0:1], 0xe8
	s_mov_b64 s[84:85], s[0:1]
	s_mov_b32 s82, s2
	s_add_u32 s2, s84, 0xe8
	v_and_b32_e32 v246, 0x3ff, v0
	s_addc_u32 s3, s85, 0
	v_cmp_eq_u32_e64 s[4:5], 0, v246
	s_and_saveexec_b64 s[0:1], s[4:5]
	s_cbranch_execz .LBB0_2
	s_add_i32 s6, 0, 0x22300
	v_mov_b32_e32 v1, 0
	v_mov_b32_e32 v2, s6
	s_add_i32 s6, 0, 0x22304
	ds_write_b32 v2, v1
	v_mov_b32_e32 v2, s6
	ds_write_b32 v2, v1
	s_add_i32 s6, 0, 0x22320
	v_mov_b32_e32 v2, s6
	ds_write_b32 v2, v1

.Lmgepi_last:
	v_mov_b64_e32 v[210:211], v[214:215]
	global_load_dwordx4 v[144:147], v[210:211], off
	global_load_dwordx4 v[148:151], v[210:211], off offset:256
	s_mov_b64 s[98:99], 0x36000
	v_lshl_add_u64 v[210:211], v[214:215], 0, s[98:99]
	global_load_dwordx4 v[152:155], v[210:211], off
	global_load_dwordx4 v[156:159], v[210:211], off offset:256
	s_mov_b64 s[98:99], 0x6c000
	v_lshl_add_u64 v[210:211], v[214:215], 0, s[98:99]
	global_load_dwordx4 v[160:163], v[210:211], off
	global_load_dwordx4 v[164:167], v[210:211], off offset:256
	s_mov_b64 s[98:99], 0xa2000
	v_lshl_add_u64 v[210:211], v[214:215], 0, s[98:99]
	global_load_dwordx4 v[170:173], v[210:211], off
	global_load_dwordx4 v[174:177], v[210:211], off offset:256
	s_waitcnt vmcnt(0)
	v_mov_b64_e32 v[210:211], v[216:217]
	v_lshlrev_b32_e32 v178, 16, v144
	v_and_b32_e32 v144, 0xffff0000, v144
	v_lshlrev_b32_e32 v179, 16, v145
	v_and_b32_e32 v145, 0xffff0000, v145
	v_lshlrev_b32_e32 v180, 16, v146
	v_and_b32_e32 v146, 0xffff0000, v146
	v_lshlrev_b32_e32 v181, 16, v147
	v_and_b32_e32 v147, 0xffff0000, v147
	v_mul_f32_e32 v178, 0xbfb8aa3b, v178
	v_mul_f32_e32 v144, 0xbfb8aa3b, v144
	v_mul_f32_e32 v179, 0xbfb8aa3b, v179
	v_mul_f32_e32 v145, 0xbfb8aa3b, v145
	v_mul_f32_e32 v180, 0xbfb8aa3b, v180
	v_mul_f32_e32 v146, 0xbfb8aa3b, v146
	v_mul_f32_e32 v181, 0xbfb8aa3b, v181
	v_mul_f32_e32 v147, 0xbfb8aa3b, v147
	v_exp_f32_e32 v178, v178
	v_exp_f32_e32 v144, v144
	v_exp_f32_e32 v179, v179
	v_exp_f32_e32 v145, v145
	v_exp_f32_e32 v180, v180
	v_exp_f32_e32 v146, v146
	v_exp_f32_e32 v181, v181
	v_exp_f32_e32 v147, v147
	v_add_f32_e32 v178, 1.0, v178
	v_add_f32_e32 v144, 1.0, v144
	v_add_f32_e32 v179, 1.0, v179
	v_add_f32_e32 v145, 1.0, v145
	v_add_f32_e32 v180, 1.0, v180
	v_add_f32_e32 v146, 1.0, v146
	v_add_f32_e32 v181, 1.0, v181
	v_add_f32_e32 v147, 1.0, v147
	v_rcp_f32_e32 v178, v178
	v_rcp_f32_e32 v144, v144
	v_rcp_f32_e32 v179, v179
	v_rcp_f32_e32 v145, v145
	v_rcp_f32_e32 v180, v180
	v_rcp_f32_e32 v146, v146
	v_rcp_f32_e32 v181, v181
	v_rcp_f32_e32 v147, v147
	s_nop 0
	v_mul_f32_e32 v186, v128, v178
	v_mul_f32_e32 v187, v129, v144
	v_mul_f32_e32 v188, v130, v179
	v_mul_f32_e32 v189, v131, v145
	v_mul_f32_e32 v190, v124, v180
	v_mul_f32_e32 v191, v125, v146
	v_mul_f32_e32 v192, v126, v181
	v_mul_f32_e32 v193, v127, v147
	v_cvt_pk_bf16_f32 v144, v186, v187
	v_cvt_pk_bf16_f32 v145, v188, v189
	v_cvt_pk_bf16_f32 v146, v190, v191
	v_cvt_pk_bf16_f32 v147, v192, v193
	global_store_dwordx4 v[210:211], v[144:147], off
	v_lshlrev_b32_e32 v178, 16, v148
	v_and_b32_e32 v148, 0xffff0000, v148
	v_lshlrev_b32_e32 v179, 16, v149
	v_and_b32_e32 v149, 0xffff0000, v149
	v_lshlrev_b32_e32 v180, 16, v150
	v_and_b32_e32 v150, 0xffff0000, v150
	v_lshlrev_b32_e32 v181, 16, v151
	v_and_b32_e32 v151, 0xffff0000, v151
	v_mul_f32_e32 v178, 0xbfb8aa3b, v178
	v_mul_f32_e32 v148, 0xbfb8aa3b, v148
	v_mul_f32_e32 v179, 0xbfb8aa3b, v179
	v_mul_f32_e32 v149, 0xbfb8aa3b, v149
	v_mul_f32_e32 v180, 0xbfb8aa3b, v180
	v_mul_f32_e32 v150, 0xbfb8aa3b, v150
	v_mul_f32_e32 v181, 0xbfb8aa3b, v181
	v_mul_f32_e32 v151, 0xbfb8aa3b, v151
	v_exp_f32_e32 v178, v178
	v_exp_f32_e32 v148, v148
	v_exp_f32_e32 v179, v179
	v_exp_f32_e32 v149, v149
	v_exp_f32_e32 v180, v180
	v_exp_f32_e32 v150, v150
	v_exp_f32_e32 v181, v181
	v_exp_f32_e32 v151, v151
	v_add_f32_e32 v178, 1.0, v178
	v_add_f32_e32 v148, 1.0, v148
	v_add_f32_e32 v179, 1.0, v179
	v_add_f32_e32 v149, 1.0, v149
	v_add_f32_e32 v180, 1.0, v180
	v_add_f32_e32 v150, 1.0, v150
	v_add_f32_e32 v181, 1.0, v181
	v_add_f32_e32 v151, 1.0, v151
	v_rcp_f32_e32 v178, v178
	v_rcp_f32_e32 v148, v148
	v_rcp_f32_e32 v179, v179
	v_rcp_f32_e32 v149, v149
	v_rcp_f32_e32 v180, v180
	v_rcp_f32_e32 v150, v150
	v_rcp_f32_e32 v181, v181
	v_rcp_f32_e32 v151, v151
	s_nop 0
	v_mul_f32_e32 v186, v92, v178
	v_mul_f32_e32 v187, v93, v148
	v_mul_f32_e32 v188, v94, v179
	v_mul_f32_e32 v189, v95, v149
	v_mul_f32_e32 v190, v88, v180
	v_mul_f32_e32 v191, v89, v150
	v_mul_f32_e32 v192, v90, v181
	v_mul_f32_e32 v193, v91, v151
	v_cvt_pk_bf16_f32 v148, v186, v187
	v_cvt_pk_bf16_f32 v149, v188, v189
	v_cvt_pk_bf16_f32 v150, v190, v191
	v_cvt_pk_bf16_f32 v151, v192, v193
	global_store_dwordx4 v[210:211], v[148:151], off offset:256
	s_mov_b64 s[98:99], 0x36000
	v_lshl_add_u64 v[210:211], v[216:217], 0, s[98:99]
	v_lshlrev_b32_e32 v178, 16, v152
	v_and_b32_e32 v152, 0xffff0000, v152
	v_lshlrev_b32_e32 v179, 16, v153
	v_and_b32_e32 v153, 0xffff0000, v153
	v_lshlrev_b32_e32 v180, 16, v154
	v_and_b32_e32 v154, 0xffff0000, v154
	v_lshlrev_b32_e32 v181, 16, v155
	v_and_b32_e32 v155, 0xffff0000, v155
	v_mul_f32_e32 v178, 0xbfb8aa3b, v178
	v_mul_f32_e32 v152, 0xbfb8aa3b, v152
	v_mul_f32_e32 v179, 0xbfb8aa3b, v179
	v_mul_f32_e32 v153, 0xbfb8aa3b, v153
	v_mul_f32_e32 v180, 0xbfb8aa3b, v180
	v_mul_f32_e32 v154, 0xbfb8aa3b, v154
	v_mul_f32_e32 v181, 0xbfb8aa3b, v181
	v_mul_f32_e32 v155, 0xbfb8aa3b, v155
	v_exp_f32_e32 v178, v178
	v_exp_f32_e32 v152, v152
	v_exp_f32_e32 v179, v179
	v_exp_f32_e32 v153, v153
	v_exp_f32_e32 v180, v180
	v_exp_f32_e32 v154, v154
	v_exp_f32_e32 v181, v181
	v_exp_f32_e32 v155, v155
	v_add_f32_e32 v178, 1.0, v178
	v_add_f32_e32 v152, 1.0, v152
	v_add_f32_e32 v179, 1.0, v179
	v_add_f32_e32 v153, 1.0, v153
	v_add_f32_e32 v180, 1.0, v180
	v_add_f32_e32 v154, 1.0, v154
	v_add_f32_e32 v181, 1.0, v181
	v_add_f32_e32 v155, 1.0, v155
	v_rcp_f32_e32 v178, v178
	v_rcp_f32_e32 v152, v152
	v_rcp_f32_e32 v179, v179
	v_rcp_f32_e32 v153, v153
	v_rcp_f32_e32 v180, v180
	v_rcp_f32_e32 v154, v154
	v_rcp_f32_e32 v181, v181
	v_rcp_f32_e32 v155, v155
	s_nop 0
	v_mul_f32_e32 v186, v120, v178
	v_mul_f32_e32 v187, v121, v152
	v_mul_f32_e32 v188, v122, v179
	v_mul_f32_e32 v189, v123, v153
	v_mul_f32_e32 v190, v116, v180
	v_mul_f32_e32 v191, v117, v154
	v_mul_f32_e32 v192, v118, v181
	v_mul_f32_e32 v193, v119, v155
	v_cvt_pk_bf16_f32 v152, v186, v187
	v_cvt_pk_bf16_f32 v153, v188, v189
	v_cvt_pk_bf16_f32 v154, v190, v191
	v_cvt_pk_bf16_f32 v155, v192, v193
	global_store_dwordx4 v[210:211], v[152:155], off
	v_lshlrev_b32_e32 v178, 16, v156
	v_and_b32_e32 v156, 0xffff0000, v156
	v_lshlrev_b32_e32 v179, 16, v157
	v_and_b32_e32 v157, 0xffff0000, v157
	v_lshlrev_b32_e32 v180, 16, v158
	v_and_b32_e32 v158, 0xffff0000, v158
	v_lshlrev_b32_e32 v181, 16, v159
	v_and_b32_e32 v159, 0xffff0000, v159
	v_mul_f32_e32 v178, 0xbfb8aa3b, v178
	v_mul_f32_e32 v156, 0xbfb8aa3b, v156
	v_mul_f32_e32 v179, 0xbfb8aa3b, v179
	v_mul_f32_e32 v157, 0xbfb8aa3b, v157
	v_mul_f32_e32 v180, 0xbfb8aa3b, v180
	v_mul_f32_e32 v158, 0xbfb8aa3b, v158
	v_mul_f32_e32 v181, 0xbfb8aa3b, v181
	v_mul_f32_e32 v159, 0xbfb8aa3b, v159
	v_exp_f32_e32 v178, v178
	v_exp_f32_e32 v156, v156
	v_exp_f32_e32 v179, v179
	v_exp_f32_e32 v157, v157
	v_exp_f32_e32 v180, v180
	v_exp_f32_e32 v158, v158
	v_exp_f32_e32 v181, v181
	v_exp_f32_e32 v159, v159
	v_add_f32_e32 v178, 1.0, v178
	v_add_f32_e32 v156, 1.0, v156
	v_add_f32_e32 v179, 1.0, v179
	v_add_f32_e32 v157, 1.0, v157
	v_add_f32_e32 v180, 1.0, v180
	v_add_f32_e32 v158, 1.0, v158
	v_add_f32_e32 v181, 1.0, v181
	v_add_f32_e32 v159, 1.0, v159
	v_rcp_f32_e32 v178, v178
	v_rcp_f32_e32 v156, v156
	v_rcp_f32_e32 v179, v179
	v_rcp_f32_e32 v157, v157
	v_rcp_f32_e32 v180, v180
	v_rcp_f32_e32 v158, v158
	v_rcp_f32_e32 v181, v181
	v_rcp_f32_e32 v159, v159
	s_nop 0
	v_mul_f32_e32 v186, v84, v178
	v_mul_f32_e32 v187, v85, v156
	v_mul_f32_e32 v188, v86, v179
	v_mul_f32_e32 v189, v87, v157
	v_mul_f32_e32 v190, v80, v180
	v_mul_f32_e32 v191, v81, v158
	v_mul_f32_e32 v192, v82, v181
	v_mul_f32_e32 v193, v83, v159
	v_cvt_pk_bf16_f32 v156, v186, v187
	v_cvt_pk_bf16_f32 v157, v188, v189
	v_cvt_pk_bf16_f32 v158, v190, v191
	v_cvt_pk_bf16_f32 v159, v192, v193
	global_store_dwordx4 v[210:211], v[156:159], off offset:256
	s_mov_b64 s[98:99], 0x6c000
	v_lshl_add_u64 v[210:211], v[216:217], 0, s[98:99]
	v_lshlrev_b32_e32 v178, 16, v160
	v_and_b32_e32 v160, 0xffff0000, v160
	v_lshlrev_b32_e32 v179, 16, v161
	v_and_b32_e32 v161, 0xffff0000, v161
	v_lshlrev_b32_e32 v180, 16, v162
	v_and_b32_e32 v162, 0xffff0000, v162
	v_lshlrev_b32_e32 v181, 16, v163
	v_and_b32_e32 v163, 0xffff0000, v163
	v_mul_f32_e32 v178, 0xbfb8aa3b, v178
	v_mul_f32_e32 v160, 0xbfb8aa3b, v160
	v_mul_f32_e32 v179, 0xbfb8aa3b, v179
	v_mul_f32_e32 v161, 0xbfb8aa3b, v161
	v_mul_f32_e32 v180, 0xbfb8aa3b, v180
	v_mul_f32_e32 v162, 0xbfb8aa3b, v162
	v_mul_f32_e32 v181, 0xbfb8aa3b, v181
	v_mul_f32_e32 v163, 0xbfb8aa3b, v163
	v_exp_f32_e32 v178, v178
	v_exp_f32_e32 v160, v160
	v_exp_f32_e32 v179, v179
	v_exp_f32_e32 v161, v161
	v_exp_f32_e32 v180, v180
	v_exp_f32_e32 v162, v162
	v_exp_f32_e32 v181, v181
	v_exp_f32_e32 v163, v163
	v_add_f32_e32 v178, 1.0, v178
	v_add_f32_e32 v160, 1.0, v160
	v_add_f32_e32 v179, 1.0, v179
	v_add_f32_e32 v161, 1.0, v161
	v_add_f32_e32 v180, 1.0, v180
	v_add_f32_e32 v162, 1.0, v162
	v_add_f32_e32 v181, 1.0, v181
	v_add_f32_e32 v163, 1.0, v163
	v_rcp_f32_e32 v178, v178
	v_rcp_f32_e32 v160, v160
	v_rcp_f32_e32 v179, v179
	v_rcp_f32_e32 v161, v161
	v_rcp_f32_e32 v180, v180
	v_rcp_f32_e32 v162, v162
	v_rcp_f32_e32 v181, v181
	v_rcp_f32_e32 v163, v163
	s_nop 0
	v_mul_f32_e32 v186, v108, v178
	v_mul_f32_e32 v187, v109, v160
	v_mul_f32_e32 v188, v110, v179
	v_mul_f32_e32 v189, v111, v161
	v_mul_f32_e32 v190, v104, v180
	v_mul_f32_e32 v191, v105, v162
	v_mul_f32_e32 v192, v106, v181
	v_mul_f32_e32 v193, v107, v163
	v_cvt_pk_bf16_f32 v160, v186, v187
	v_cvt_pk_bf16_f32 v161, v188, v189
	v_cvt_pk_bf16_f32 v162, v190, v191
	v_cvt_pk_bf16_f32 v163, v192, v193
	global_store_dwordx4 v[210:211], v[160:163], off
	v_lshlrev_b32_e32 v178, 16, v164
	v_and_b32_e32 v164, 0xffff0000, v164
	v_lshlrev_b32_e32 v179, 16, v165
	v_and_b32_e32 v165, 0xffff0000, v165
	v_lshlrev_b32_e32 v180, 16, v166
	v_and_b32_e32 v166, 0xffff0000, v166
	v_lshlrev_b32_e32 v181, 16, v167
	v_and_b32_e32 v167, 0xffff0000, v167
	v_mul_f32_e32 v178, 0xbfb8aa3b, v178
	v_mul_f32_e32 v164, 0xbfb8aa3b, v164
	v_mul_f32_e32 v179, 0xbfb8aa3b, v179
	v_mul_f32_e32 v165, 0xbfb8aa3b, v165
	v_mul_f32_e32 v180, 0xbfb8aa3b, v180
	v_mul_f32_e32 v166, 0xbfb8aa3b, v166
	v_mul_f32_e32 v181, 0xbfb8aa3b, v181
	v_mul_f32_e32 v167, 0xbfb8aa3b, v167
	v_exp_f32_e32 v178, v178
	v_exp_f32_e32 v164, v164
	v_exp_f32_e32 v179, v179
	v_exp_f32_e32 v165, v165
	v_exp_f32_e32 v180, v180
	v_exp_f32_e32 v166, v166
	v_exp_f32_e32 v181, v181
	v_exp_f32_e32 v167, v167
	v_add_f32_e32 v178, 1.0, v178
	v_add_f32_e32 v164, 1.0, v164
	v_add_f32_e32 v179, 1.0, v179
	v_add_f32_e32 v165, 1.0, v165
	v_add_f32_e32 v180, 1.0, v180
	v_add_f32_e32 v166, 1.0, v166
	v_add_f32_e32 v181, 1.0, v181
	v_add_f32_e32 v167, 1.0, v167
	v_rcp_f32_e32 v178, v178
	v_rcp_f32_e32 v164, v164
	v_rcp_f32_e32 v179, v179
	v_rcp_f32_e32 v165, v165
	v_rcp_f32_e32 v180, v180
	v_rcp_f32_e32 v166, v166
	v_rcp_f32_e32 v181, v181
	v_rcp_f32_e32 v167, v167
	s_nop 0
	v_mul_f32_e32 v186, v76, v178
	v_mul_f32_e32 v187, v77, v164
	v_mul_f32_e32 v188, v78, v179
	v_mul_f32_e32 v189, v79, v165
	v_mul_f32_e32 v190, v72, v180
	v_mul_f32_e32 v191, v73, v166
	v_mul_f32_e32 v192, v74, v181
	v_mul_f32_e32 v193, v75, v167
	v_cvt_pk_bf16_f32 v164, v186, v187
	v_cvt_pk_bf16_f32 v165, v188, v189
	v_cvt_pk_bf16_f32 v166, v190, v191
	v_cvt_pk_bf16_f32 v167, v192, v193
	global_store_dwordx4 v[210:211], v[164:167], off offset:256
	s_mov_b64 s[98:99], 0xa2000
	v_lshl_add_u64 v[210:211], v[216:217], 0, s[98:99]
	v_lshlrev_b32_e32 v178, 16, v170
	v_and_b32_e32 v170, 0xffff0000, v170
	v_lshlrev_b32_e32 v179, 16, v171
	v_and_b32_e32 v171, 0xffff0000, v171
	v_lshlrev_b32_e32 v180, 16, v172
	v_and_b32_e32 v172, 0xffff0000, v172
	v_lshlrev_b32_e32 v181, 16, v173
	v_and_b32_e32 v173, 0xffff0000, v173
	v_mul_f32_e32 v178, 0xbfb8aa3b, v178
	v_mul_f32_e32 v170, 0xbfb8aa3b, v170
	v_mul_f32_e32 v179, 0xbfb8aa3b, v179
	v_mul_f32_e32 v171, 0xbfb8aa3b, v171
	v_mul_f32_e32 v180, 0xbfb8aa3b, v180
	v_mul_f32_e32 v172, 0xbfb8aa3b, v172
	v_mul_f32_e32 v181, 0xbfb8aa3b, v181
	v_mul_f32_e32 v173, 0xbfb8aa3b, v173
	v_exp_f32_e32 v178, v178
	v_exp_f32_e32 v170, v170
	v_exp_f32_e32 v179, v179
	v_exp_f32_e32 v171, v171
	v_exp_f32_e32 v180, v180
	v_exp_f32_e32 v172, v172
	v_exp_f32_e32 v181, v181
	v_exp_f32_e32 v173, v173
	v_add_f32_e32 v178, 1.0, v178
	v_add_f32_e32 v170, 1.0, v170
	v_add_f32_e32 v179, 1.0, v179
	v_add_f32_e32 v171, 1.0, v171
	v_add_f32_e32 v180, 1.0, v180
	v_add_f32_e32 v172, 1.0, v172
	v_add_f32_e32 v181, 1.0, v181
	v_add_f32_e32 v173, 1.0, v173
	v_rcp_f32_e32 v178, v178
	v_rcp_f32_e32 v170, v170
	v_rcp_f32_e32 v179, v179
	v_rcp_f32_e32 v171, v171
	v_rcp_f32_e32 v180, v180
	v_rcp_f32_e32 v172, v172
	v_rcp_f32_e32 v181, v181
	v_rcp_f32_e32 v173, v173
	s_nop 0
	v_mul_f32_e32 v186, v100, v178
	v_mul_f32_e32 v187, v101, v170
	v_mul_f32_e32 v188, v102, v179
	v_mul_f32_e32 v189, v103, v171
	v_mul_f32_e32 v190, v96, v180
	v_mul_f32_e32 v191, v97, v172
	v_mul_f32_e32 v192, v98, v181
	v_mul_f32_e32 v193, v99, v173
	v_cvt_pk_bf16_f32 v170, v186, v187
	v_cvt_pk_bf16_f32 v171, v188, v189
	v_cvt_pk_bf16_f32 v172, v190, v191
	v_cvt_pk_bf16_f32 v173, v192, v193
	global_store_dwordx4 v[210:211], v[170:173], off
	v_lshlrev_b32_e32 v178, 16, v174
	v_and_b32_e32 v174, 0xffff0000, v174
	v_lshlrev_b32_e32 v179, 16, v175
	v_and_b32_e32 v175, 0xffff0000, v175
	v_lshlrev_b32_e32 v180, 16, v176
	v_and_b32_e32 v176, 0xffff0000, v176
	v_lshlrev_b32_e32 v181, 16, v177
	v_and_b32_e32 v177, 0xffff0000, v177
	v_mul_f32_e32 v178, 0xbfb8aa3b, v178
	v_mul_f32_e32 v174, 0xbfb8aa3b, v174
	v_mul_f32_e32 v179, 0xbfb8aa3b, v179
	v_mul_f32_e32 v175, 0xbfb8aa3b, v175
	v_mul_f32_e32 v180, 0xbfb8aa3b, v180
	v_mul_f32_e32 v176, 0xbfb8aa3b, v176
	v_mul_f32_e32 v181, 0xbfb8aa3b, v181
	v_mul_f32_e32 v177, 0xbfb8aa3b, v177
	v_exp_f32_e32 v178, v178
	v_exp_f32_e32 v174, v174
	v_exp_f32_e32 v179, v179
	v_exp_f32_e32 v175, v175
	v_exp_f32_e32 v180, v180
	v_exp_f32_e32 v176, v176
	v_exp_f32_e32 v181, v181
	v_exp_f32_e32 v177, v177
	v_add_f32_e32 v178, 1.0, v178
	v_add_f32_e32 v174, 1.0, v174
	v_add_f32_e32 v179, 1.0, v179
	v_add_f32_e32 v175, 1.0, v175
	v_add_f32_e32 v180, 1.0, v180
	v_add_f32_e32 v176, 1.0, v176
	v_add_f32_e32 v181, 1.0, v181
	v_add_f32_e32 v177, 1.0, v177
	v_rcp_f32_e32 v178, v178
	v_rcp_f32_e32 v174, v174
	v_rcp_f32_e32 v179, v179
	v_rcp_f32_e32 v175, v175
	v_rcp_f32_e32 v180, v180
	v_rcp_f32_e32 v176, v176
	v_rcp_f32_e32 v181, v181
	v_rcp_f32_e32 v177, v177
	s_nop 0
	v_mul_f32_e32 v186, v68, v178
	v_mul_f32_e32 v187, v69, v174
	v_mul_f32_e32 v188, v70, v179
	v_mul_f32_e32 v189, v71, v175
	v_mul_f32_e32 v190, v64, v180
	v_mul_f32_e32 v191, v65, v176
	v_mul_f32_e32 v192, v66, v181
	v_mul_f32_e32 v193, v67, v177
	v_cvt_pk_bf16_f32 v174, v186, v187
	v_cvt_pk_bf16_f32 v175, v188, v189
	v_cvt_pk_bf16_f32 v176, v190, v191
	v_cvt_pk_bf16_f32 v177, v192, v193
	global_store_dwordx4 v[210:211], v[174:177], off offset:256
	s_mov_b64 s[98:99], 0x1b0000
	v_lshl_add_u64 v[210:211], v[214:215], 0, s[98:99]
	global_load_dwordx4 v[144:147], v[210:211], off
	global_load_dwordx4 v[148:151], v[210:211], off offset:256
	s_mov_b64 s[98:99], 0x1e6000
	v_lshl_add_u64 v[210:211], v[214:215], 0, s[98:99]
	global_load_dwordx4 v[152:155], v[210:211], off
	global_load_dwordx4 v[156:159], v[210:211], off offset:256
	s_mov_b64 s[98:99], 0x21c000
	v_lshl_add_u64 v[210:211], v[214:215], 0, s[98:99]
	global_load_dwordx4 v[160:163], v[210:211], off
	global_load_dwordx4 v[164:167], v[210:211], off offset:256
	s_mov_b64 s[98:99], 0x252000
	v_lshl_add_u64 v[210:211], v[214:215], 0, s[98:99]
	global_load_dwordx4 v[170:173], v[210:211], off
	global_load_dwordx4 v[174:177], v[210:211], off offset:256
	s_waitcnt vmcnt(0)
	s_mov_b64 s[98:99], 0x1b0000
	v_lshl_add_u64 v[210:211], v[216:217], 0, s[98:99]
	v_lshlrev_b32_e32 v178, 16, v144
	v_and_b32_e32 v144, 0xffff0000, v144
	v_lshlrev_b32_e32 v179, 16, v145
	v_and_b32_e32 v145, 0xffff0000, v145
	v_lshlrev_b32_e32 v180, 16, v146
	v_and_b32_e32 v146, 0xffff0000, v146
	v_lshlrev_b32_e32 v181, 16, v147
	v_and_b32_e32 v147, 0xffff0000, v147
	v_mul_f32_e32 v178, 0xbfb8aa3b, v178
	v_mul_f32_e32 v144, 0xbfb8aa3b, v144
	v_mul_f32_e32 v179, 0xbfb8aa3b, v179
	v_mul_f32_e32 v145, 0xbfb8aa3b, v145
	v_mul_f32_e32 v180, 0xbfb8aa3b, v180
	v_mul_f32_e32 v146, 0xbfb8aa3b, v146
	v_mul_f32_e32 v181, 0xbfb8aa3b, v181
	v_mul_f32_e32 v147, 0xbfb8aa3b, v147
	v_exp_f32_e32 v178, v178
	v_exp_f32_e32 v144, v144
	v_exp_f32_e32 v179, v179
	v_exp_f32_e32 v145, v145
	v_exp_f32_e32 v180, v180
	v_exp_f32_e32 v146, v146
	v_exp_f32_e32 v181, v181
	v_exp_f32_e32 v147, v147
	v_add_f32_e32 v178, 1.0, v178
	v_add_f32_e32 v144, 1.0, v144
	v_add_f32_e32 v179, 1.0, v179
	v_add_f32_e32 v145, 1.0, v145
	v_add_f32_e32 v180, 1.0, v180
	v_add_f32_e32 v146, 1.0, v146
	v_add_f32_e32 v181, 1.0, v181
	v_add_f32_e32 v147, 1.0, v147
	v_rcp_f32_e32 v178, v178
	v_rcp_f32_e32 v144, v144
	v_rcp_f32_e32 v179, v179
	v_rcp_f32_e32 v145, v145
	v_rcp_f32_e32 v180, v180
	v_rcp_f32_e32 v146, v146
	v_rcp_f32_e32 v181, v181
	v_rcp_f32_e32 v147, v147
	s_nop 0
	v_mul_f32_e32 v186, v60, v178
	v_mul_f32_e32 v187, v61, v144
	v_mul_f32_e32 v188, v62, v179
	v_mul_f32_e32 v189, v63, v145
	v_mul_f32_e32 v190, v56, v180
	v_mul_f32_e32 v191, v57, v146
	v_mul_f32_e32 v192, v58, v181
	v_mul_f32_e32 v193, v59, v147
	v_cvt_pk_bf16_f32 v144, v186, v187
	v_cvt_pk_bf16_f32 v145, v188, v189
	v_cvt_pk_bf16_f32 v146, v190, v191
	v_cvt_pk_bf16_f32 v147, v192, v193
	global_store_dwordx4 v[210:211], v[144:147], off
	v_lshlrev_b32_e32 v178, 16, v148
	v_and_b32_e32 v148, 0xffff0000, v148
	v_lshlrev_b32_e32 v179, 16, v149
	v_and_b32_e32 v149, 0xffff0000, v149
	v_lshlrev_b32_e32 v180, 16, v150
	v_and_b32_e32 v150, 0xffff0000, v150
	v_lshlrev_b32_e32 v181, 16, v151
	v_and_b32_e32 v151, 0xffff0000, v151
	v_mul_f32_e32 v178, 0xbfb8aa3b, v178
	v_mul_f32_e32 v148, 0xbfb8aa3b, v148
	v_mul_f32_e32 v179, 0xbfb8aa3b, v179
	v_mul_f32_e32 v149, 0xbfb8aa3b, v149
	v_mul_f32_e32 v180, 0xbfb8aa3b, v180
	v_mul_f32_e32 v150, 0xbfb8aa3b, v150
	v_mul_f32_e32 v181, 0xbfb8aa3b, v181
	v_mul_f32_e32 v151, 0xbfb8aa3b, v151
	v_exp_f32_e32 v178, v178
	v_exp_f32_e32 v148, v148
	v_exp_f32_e32 v179, v179
	v_exp_f32_e32 v149, v149
	v_exp_f32_e32 v180, v180
	v_exp_f32_e32 v150, v150
	v_exp_f32_e32 v181, v181
	v_exp_f32_e32 v151, v151
	v_add_f32_e32 v178, 1.0, v178
	v_add_f32_e32 v148, 1.0, v148
	v_add_f32_e32 v179, 1.0, v179
	v_add_f32_e32 v149, 1.0, v149
	v_add_f32_e32 v180, 1.0, v180
	v_add_f32_e32 v150, 1.0, v150
	v_add_f32_e32 v181, 1.0, v181
	v_add_f32_e32 v151, 1.0, v151
	v_rcp_f32_e32 v178, v178
	v_rcp_f32_e32 v148, v148
	v_rcp_f32_e32 v179, v179
	v_rcp_f32_e32 v149, v149
	v_rcp_f32_e32 v180, v180
	v_rcp_f32_e32 v150, v150
	v_rcp_f32_e32 v181, v181
	v_rcp_f32_e32 v151, v151
	s_nop 0
	v_mul_f32_e32 v186, v28, v178
	v_mul_f32_e32 v187, v29, v148
	v_mul_f32_e32 v188, v30, v179
	v_mul_f32_e32 v189, v31, v149
	v_mul_f32_e32 v190, v24, v180
	v_mul_f32_e32 v191, v25, v150
	v_mul_f32_e32 v192, v26, v181
	v_mul_f32_e32 v193, v27, v151
	v_cvt_pk_bf16_f32 v148, v186, v187
	v_cvt_pk_bf16_f32 v149, v188, v189
	v_cvt_pk_bf16_f32 v150, v190, v191
	v_cvt_pk_bf16_f32 v151, v192, v193
	global_store_dwordx4 v[210:211], v[148:151], off offset:256
	s_mov_b64 s[98:99], 0x1e6000
	v_lshl_add_u64 v[210:211], v[216:217], 0, s[98:99]
	v_lshlrev_b32_e32 v178, 16, v152
	v_and_b32_e32 v152, 0xffff0000, v152
	v_lshlrev_b32_e32 v179, 16, v153
	v_and_b32_e32 v153, 0xffff0000, v153
	v_lshlrev_b32_e32 v180, 16, v154
	v_and_b32_e32 v154, 0xffff0000, v154
	v_lshlrev_b32_e32 v181, 16, v155
	v_and_b32_e32 v155, 0xffff0000, v155
	v_mul_f32_e32 v178, 0xbfb8aa3b, v178
	v_mul_f32_e32 v152, 0xbfb8aa3b, v152
	v_mul_f32_e32 v179, 0xbfb8aa3b, v179
	v_mul_f32_e32 v153, 0xbfb8aa3b, v153
	v_mul_f32_e32 v180, 0xbfb8aa3b, v180
	v_mul_f32_e32 v154, 0xbfb8aa3b, v154
	v_mul_f32_e32 v181, 0xbfb8aa3b, v181
	v_mul_f32_e32 v155, 0xbfb8aa3b, v155
	v_exp_f32_e32 v178, v178
	v_exp_f32_e32 v152, v152
	v_exp_f32_e32 v179, v179
	v_exp_f32_e32 v153, v153
	v_exp_f32_e32 v180, v180
	v_exp_f32_e32 v154, v154
	v_exp_f32_e32 v181, v181
	v_exp_f32_e32 v155, v155
	v_add_f32_e32 v178, 1.0, v178
	v_add_f32_e32 v152, 1.0, v152
	v_add_f32_e32 v179, 1.0, v179
	v_add_f32_e32 v153, 1.0, v153
	v_add_f32_e32 v180, 1.0, v180
	v_add_f32_e32 v154, 1.0, v154
	v_add_f32_e32 v181, 1.0, v181
	v_add_f32_e32 v155, 1.0, v155
	v_rcp_f32_e32 v178, v178
	v_rcp_f32_e32 v152, v152
	v_rcp_f32_e32 v179, v179
	v_rcp_f32_e32 v153, v153
	v_rcp_f32_e32 v180, v180
	v_rcp_f32_e32 v154, v154
	v_rcp_f32_e32 v181, v181
	v_rcp_f32_e32 v155, v155
	s_nop 0
	v_mul_f32_e32 v186, v52, v178
	v_mul_f32_e32 v187, v53, v152
	v_mul_f32_e32 v188, v54, v179
	v_mul_f32_e32 v189, v55, v153
	v_mul_f32_e32 v190, v48, v180
	v_mul_f32_e32 v191, v49, v154
	v_mul_f32_e32 v192, v50, v181
	v_mul_f32_e32 v193, v51, v155
	v_cvt_pk_bf16_f32 v152, v186, v187
	v_cvt_pk_bf16_f32 v153, v188, v189
	v_cvt_pk_bf16_f32 v154, v190, v191
	v_cvt_pk_bf16_f32 v155, v192, v193
	global_store_dwordx4 v[210:211], v[152:155], off
	v_lshlrev_b32_e32 v178, 16, v156
	v_and_b32_e32 v156, 0xffff0000, v156
	v_lshlrev_b32_e32 v179, 16, v157
	v_and_b32_e32 v157, 0xffff0000, v157
	v_lshlrev_b32_e32 v180, 16, v158
	v_and_b32_e32 v158, 0xffff0000, v158
	v_lshlrev_b32_e32 v181, 16, v159
	v_and_b32_e32 v159, 0xffff0000, v159
	v_mul_f32_e32 v178, 0xbfb8aa3b, v178
	v_mul_f32_e32 v156, 0xbfb8aa3b, v156
	v_mul_f32_e32 v179, 0xbfb8aa3b, v179
	v_mul_f32_e32 v157, 0xbfb8aa3b, v157
	v_mul_f32_e32 v180, 0xbfb8aa3b, v180
	v_mul_f32_e32 v158, 0xbfb8aa3b, v158
	v_mul_f32_e32 v181, 0xbfb8aa3b, v181
	v_mul_f32_e32 v159, 0xbfb8aa3b, v159
	v_exp_f32_e32 v178, v178
	v_exp_f32_e32 v156, v156
	v_exp_f32_e32 v179, v179
	v_exp_f32_e32 v157, v157
	v_exp_f32_e32 v180, v180
	v_exp_f32_e32 v158, v158
	v_exp_f32_e32 v181, v181
	v_exp_f32_e32 v159, v159
	v_add_f32_e32 v178, 1.0, v178
	v_add_f32_e32 v156, 1.0, v156
	v_add_f32_e32 v179, 1.0, v179
	v_add_f32_e32 v157, 1.0, v157
	v_add_f32_e32 v180, 1.0, v180
	v_add_f32_e32 v158, 1.0, v158
	v_add_f32_e32 v181, 1.0, v181
	v_add_f32_e32 v159, 1.0, v159
	v_rcp_f32_e32 v178, v178
	v_rcp_f32_e32 v156, v156
	v_rcp_f32_e32 v179, v179
	v_rcp_f32_e32 v157, v157
	v_rcp_f32_e32 v180, v180
	v_rcp_f32_e32 v158, v158
	v_rcp_f32_e32 v181, v181
	v_rcp_f32_e32 v159, v159
	s_nop 0
	v_mul_f32_e32 v186, v20, v178
	v_mul_f32_e32 v187, v21, v156
	v_mul_f32_e32 v188, v22, v179
	v_mul_f32_e32 v189, v23, v157
	v_mul_f32_e32 v190, v16, v180
	v_mul_f32_e32 v191, v17, v158
	v_mul_f32_e32 v192, v18, v181
	v_mul_f32_e32 v193, v19, v159
	v_cvt_pk_bf16_f32 v156, v186, v187
	v_cvt_pk_bf16_f32 v157, v188, v189
	v_cvt_pk_bf16_f32 v158, v190, v191
	v_cvt_pk_bf16_f32 v159, v192, v193
	global_store_dwordx4 v[210:211], v[156:159], off offset:256
	s_mov_b64 s[98:99], 0x21c000
	v_lshl_add_u64 v[210:211], v[216:217], 0, s[98:99]
	v_lshlrev_b32_e32 v178, 16, v160
	v_and_b32_e32 v160, 0xffff0000, v160
	v_lshlrev_b32_e32 v179, 16, v161
	v_and_b32_e32 v161, 0xffff0000, v161
	v_lshlrev_b32_e32 v180, 16, v162
	v_and_b32_e32 v162, 0xffff0000, v162
	v_lshlrev_b32_e32 v181, 16, v163
	v_and_b32_e32 v163, 0xffff0000, v163
	v_mul_f32_e32 v178, 0xbfb8aa3b, v178
	v_mul_f32_e32 v160, 0xbfb8aa3b, v160
	v_mul_f32_e32 v179, 0xbfb8aa3b, v179
	v_mul_f32_e32 v161, 0xbfb8aa3b, v161
	v_mul_f32_e32 v180, 0xbfb8aa3b, v180
	v_mul_f32_e32 v162, 0xbfb8aa3b, v162
	v_mul_f32_e32 v181, 0xbfb8aa3b, v181
	v_mul_f32_e32 v163, 0xbfb8aa3b, v163
	v_exp_f32_e32 v178, v178
	v_exp_f32_e32 v160, v160
	v_exp_f32_e32 v179, v179
	v_exp_f32_e32 v161, v161
	v_exp_f32_e32 v180, v180
	v_exp_f32_e32 v162, v162
	v_exp_f32_e32 v181, v181
	v_exp_f32_e32 v163, v163
	v_add_f32_e32 v178, 1.0, v178
	v_add_f32_e32 v160, 1.0, v160
	v_add_f32_e32 v179, 1.0, v179
	v_add_f32_e32 v161, 1.0, v161
	v_add_f32_e32 v180, 1.0, v180
	v_add_f32_e32 v162, 1.0, v162
	v_add_f32_e32 v181, 1.0, v181
	v_add_f32_e32 v163, 1.0, v163
	v_rcp_f32_e32 v178, v178
	v_rcp_f32_e32 v160, v160
	v_rcp_f32_e32 v179, v179
	v_rcp_f32_e32 v161, v161
	v_rcp_f32_e32 v180, v180
	v_rcp_f32_e32 v162, v162
	v_rcp_f32_e32 v181, v181
	v_rcp_f32_e32 v163, v163
	s_nop 0
	v_mul_f32_e32 v186, v44, v178
	v_mul_f32_e32 v187, v45, v160
	v_mul_f32_e32 v188, v46, v179
	v_mul_f32_e32 v189, v47, v161
	v_mul_f32_e32 v190, v40, v180
	v_mul_f32_e32 v191, v41, v162
	v_mul_f32_e32 v192, v42, v181
	v_mul_f32_e32 v193, v43, v163
	v_cvt_pk_bf16_f32 v160, v186, v187
	v_cvt_pk_bf16_f32 v161, v188, v189
	v_cvt_pk_bf16_f32 v162, v190, v191
	v_cvt_pk_bf16_f32 v163, v192, v193
	global_store_dwordx4 v[210:211], v[160:163], off
	v_lshlrev_b32_e32 v178, 16, v164
	v_and_b32_e32 v164, 0xffff0000, v164
	v_lshlrev_b32_e32 v179, 16, v165
	v_and_b32_e32 v165, 0xffff0000, v165
	v_lshlrev_b32_e32 v180, 16, v166
	v_and_b32_e32 v166, 0xffff0000, v166
	v_lshlrev_b32_e32 v181, 16, v167
	v_and_b32_e32 v167, 0xffff0000, v167
	v_mul_f32_e32 v178, 0xbfb8aa3b, v178
	v_mul_f32_e32 v164, 0xbfb8aa3b, v164
	v_mul_f32_e32 v179, 0xbfb8aa3b, v179
	v_mul_f32_e32 v165, 0xbfb8aa3b, v165
	v_mul_f32_e32 v180, 0xbfb8aa3b, v180
	v_mul_f32_e32 v166, 0xbfb8aa3b, v166
	v_mul_f32_e32 v181, 0xbfb8aa3b, v181
	v_mul_f32_e32 v167, 0xbfb8aa3b, v167
	v_exp_f32_e32 v178, v178
	v_exp_f32_e32 v164, v164
	v_exp_f32_e32 v179, v179
	v_exp_f32_e32 v165, v165
	v_exp_f32_e32 v180, v180
	v_exp_f32_e32 v166, v166
	v_exp_f32_e32 v181, v181
	v_exp_f32_e32 v167, v167
	v_add_f32_e32 v178, 1.0, v178
	v_add_f32_e32 v164, 1.0, v164
	v_add_f32_e32 v179, 1.0, v179
	v_add_f32_e32 v165, 1.0, v165
	v_add_f32_e32 v180, 1.0, v180
	v_add_f32_e32 v166, 1.0, v166
	v_add_f32_e32 v181, 1.0, v181
	v_add_f32_e32 v167, 1.0, v167
	v_rcp_f32_e32 v178, v178
	v_rcp_f32_e32 v164, v164
	v_rcp_f32_e32 v179, v179
	v_rcp_f32_e32 v165, v165
	v_rcp_f32_e32 v180, v180
	v_rcp_f32_e32 v166, v166
	v_rcp_f32_e32 v181, v181
	v_rcp_f32_e32 v167, v167
	s_nop 0
	v_mul_f32_e32 v186, v12, v178
	v_mul_f32_e32 v187, v13, v164
	v_mul_f32_e32 v188, v14, v179
	v_mul_f32_e32 v189, v15, v165
	v_mul_f32_e32 v190, v8, v180
	v_mul_f32_e32 v191, v9, v166
	v_mul_f32_e32 v192, v10, v181
	v_mul_f32_e32 v193, v11, v167
	v_cvt_pk_bf16_f32 v164, v186, v187
	v_cvt_pk_bf16_f32 v165, v188, v189
	v_cvt_pk_bf16_f32 v166, v190, v191
	v_cvt_pk_bf16_f32 v167, v192, v193
	global_store_dwordx4 v[210:211], v[164:167], off offset:256
	s_mov_b64 s[98:99], 0x252000
	v_lshl_add_u64 v[210:211], v[216:217], 0, s[98:99]
	v_lshlrev_b32_e32 v178, 16, v170
	v_and_b32_e32 v170, 0xffff0000, v170
	v_lshlrev_b32_e32 v179, 16, v171
	v_and_b32_e32 v171, 0xffff0000, v171
	v_lshlrev_b32_e32 v180, 16, v172
	v_and_b32_e32 v172, 0xffff0000, v172
	v_lshlrev_b32_e32 v181, 16, v173
	v_and_b32_e32 v173, 0xffff0000, v173
	v_mul_f32_e32 v178, 0xbfb8aa3b, v178
	v_mul_f32_e32 v170, 0xbfb8aa3b, v170
	v_mul_f32_e32 v179, 0xbfb8aa3b, v179
	v_mul_f32_e32 v171, 0xbfb8aa3b, v171
	v_mul_f32_e32 v180, 0xbfb8aa3b, v180
	v_mul_f32_e32 v172, 0xbfb8aa3b, v172
	v_mul_f32_e32 v181, 0xbfb8aa3b, v181
	v_mul_f32_e32 v173, 0xbfb8aa3b, v173
	v_exp_f32_e32 v178, v178
	v_exp_f32_e32 v170, v170
	v_exp_f32_e32 v179, v179
	v_exp_f32_e32 v171, v171
	v_exp_f32_e32 v180, v180
	v_exp_f32_e32 v172, v172
	v_exp_f32_e32 v181, v181
	v_exp_f32_e32 v173, v173
	v_add_f32_e32 v178, 1.0, v178
	v_add_f32_e32 v170, 1.0, v170
	v_add_f32_e32 v179, 1.0, v179
	v_add_f32_e32 v171, 1.0, v171
	v_add_f32_e32 v180, 1.0, v180
	v_add_f32_e32 v172, 1.0, v172
	v_add_f32_e32 v181, 1.0, v181
	v_add_f32_e32 v173, 1.0, v173
	v_rcp_f32_e32 v178, v178
	v_rcp_f32_e32 v170, v170
	v_rcp_f32_e32 v179, v179
	v_rcp_f32_e32 v171, v171
	v_rcp_f32_e32 v180, v180
	v_rcp_f32_e32 v172, v172
	v_rcp_f32_e32 v181, v181
	v_rcp_f32_e32 v173, v173
	s_nop 0
	v_mul_f32_e32 v186, v36, v178
	v_mul_f32_e32 v187, v37, v170
	v_mul_f32_e32 v188, v38, v179
	v_mul_f32_e32 v189, v39, v171
	v_mul_f32_e32 v190, v32, v180
	v_mul_f32_e32 v191, v33, v172
	v_mul_f32_e32 v192, v34, v181
	v_mul_f32_e32 v193, v35, v173
	v_cvt_pk_bf16_f32 v170, v186, v187
	v_cvt_pk_bf16_f32 v171, v188, v189
	v_cvt_pk_bf16_f32 v172, v190, v191
	v_cvt_pk_bf16_f32 v173, v192, v193
	global_store_dwordx4 v[210:211], v[170:173], off
	v_lshlrev_b32_e32 v178, 16, v174
	v_and_b32_e32 v174, 0xffff0000, v174
	v_lshlrev_b32_e32 v179, 16, v175
	v_and_b32_e32 v175, 0xffff0000, v175
	v_lshlrev_b32_e32 v180, 16, v176
	v_and_b32_e32 v176, 0xffff0000, v176
	v_lshlrev_b32_e32 v181, 16, v177
	v_and_b32_e32 v177, 0xffff0000, v177
	v_mul_f32_e32 v178, 0xbfb8aa3b, v178
	v_mul_f32_e32 v174, 0xbfb8aa3b, v174
	v_mul_f32_e32 v179, 0xbfb8aa3b, v179
	v_mul_f32_e32 v175, 0xbfb8aa3b, v175
	v_mul_f32_e32 v180, 0xbfb8aa3b, v180
	v_mul_f32_e32 v176, 0xbfb8aa3b, v176
	v_mul_f32_e32 v181, 0xbfb8aa3b, v181
	v_mul_f32_e32 v177, 0xbfb8aa3b, v177
	v_exp_f32_e32 v178, v178
	v_exp_f32_e32 v174, v174
	v_exp_f32_e32 v179, v179
	v_exp_f32_e32 v175, v175
	v_exp_f32_e32 v180, v180
	v_exp_f32_e32 v176, v176
	v_exp_f32_e32 v181, v181
	v_exp_f32_e32 v177, v177
	v_add_f32_e32 v178, 1.0, v178
	v_add_f32_e32 v174, 1.0, v174
	v_add_f32_e32 v179, 1.0, v179
	v_add_f32_e32 v175, 1.0, v175
	v_add_f32_e32 v180, 1.0, v180
	v_add_f32_e32 v176, 1.0, v176
	v_add_f32_e32 v181, 1.0, v181
	v_add_f32_e32 v177, 1.0, v177
	v_rcp_f32_e32 v178, v178
	v_rcp_f32_e32 v174, v174
	v_rcp_f32_e32 v179, v179
	v_rcp_f32_e32 v175, v175
	v_rcp_f32_e32 v180, v180
	v_rcp_f32_e32 v176, v176
	v_rcp_f32_e32 v181, v181
	v_rcp_f32_e32 v177, v177
	s_nop 0
	v_mul_f32_e32 v186, v4, v178
	v_mul_f32_e32 v187, v5, v174
	v_mul_f32_e32 v188, v6, v179
	v_mul_f32_e32 v189, v7, v175
	v_mul_f32_e32 v190, v0, v180
	v_mul_f32_e32 v191, v1, v176
	v_mul_f32_e32 v192, v2, v181
	v_mul_f32_e32 v193, v3, v177
	v_cvt_pk_bf16_f32 v174, v186, v187
	v_cvt_pk_bf16_f32 v175, v188, v189
	v_cvt_pk_bf16_f32 v176, v190, v191
	v_cvt_pk_bf16_f32 v177, v192, v193
	global_store_dwordx4 v[210:211], v[174:177], off offset:256
	v_readlane_b32 s98, v254, 40
	s_nop 3
	s_cmp_lg_u32 s98, 0
	s_cbranch_scc1 .Lmgepi_done
	s_waitcnt vmcnt(0)
	s_mov_b64 s[6:7], exec
	s_mov_b64 exec, 1
	v_mov_b32_e32 v178, 0x22320
	v_mov_b32_e32 v179, 1
	ds_add_rtn_u32 v178, v178, v179
	s_waitcnt lgkmcnt(0)
	v_readfirstlane_b32 s98, v178
	s_and_b32 s98, s98, 7
	s_cmp_lg_u32 s98, 7
	s_cbranch_scc1 .Lmgepi_pub_skip
	buffer_wbl2 sc1
	s_waitcnt vmcnt(0)
	v_readlane_b32 s98, v255, 30
	s_nop 3
	s_cmp_lg_u32 s98, 0
	s_cselect_b32 s98, 0x200, 0
	s_add_u32 s98, s98, 0x8000
	s_lshl_b32 s99, s60, 2
	s_add_u32 s99, s98, s99
	s_add_u32 s98, s88, s99
	s_addc_u32 s99, s89, 0
	s_nop 4
	global_atomic_add v113, v179, s[98:99]
.Lmgepi_pub_skip:
	s_mov_b64 exec, s[6:7]

.LBB0_1491:
	s_waitcnt vmcnt(0)
	s_waitcnt lgkmcnt(0)
	s_barrier
	v_readlane_b32 s98, v254, 40
	s_nop 3
	s_cmp_lg_u32 s98, 0
	s_cbranch_scc1 .Lmg_gsync_do
	s_mov_b64 s[2:3], exec
	v_readlane_b32 s30, v254, 42
	v_readlane_b32 s31, v254, 43
	s_branch .LBB0_1543
.Lmg_gsync_do:
	s_and_saveexec_b64 s[2:3], s[4:5]
	v_readlane_b32 s30, v254, 42
	v_readlane_b32 s31, v254, 43
	s_cbranch_execz .LBB0_1543
	v_readlane_b32 s6, v254, 29
	s_waitcnt vmcnt(0) expcnt(0) lgkmcnt(0)
	s_nop 0
	v_mov_b32_e32 v0, s6
	ds_read_b32 v2, v0
	v_readlane_b32 s6, v254, 30
	s_waitcnt lgkmcnt(0)
	v_cmp_ne_u32_e32 vcc, 0, v2
	v_mov_b32_e32 v0, s6
	ds_read_b32 v0, v0
	s_cbranch_vccnz .LBB0_1507
	s_mov_b32 s12, 1
	s_branch .LBB0_1495

.LBB0_1547:
	v_readlane_b32 s98, v255, 12
	v_readlane_b32 s99, v255, 13
	s_nop 1
	v_writelane_b32 v255, s98, 52
	v_writelane_b32 v255, s99, 53
	v_readlane_b32 s98, v255, 15
	v_readlane_b32 s99, v255, 16
	s_nop 1
	v_writelane_b32 v255, s98, 54
	v_writelane_b32 v255, s99, 55
	v_readlane_b32 s98, v255, 8
	s_nop 1
	v_writelane_b32 v255, s98, 56
	v_writelane_b32 v255, s82, 57
	v_writelane_b32 v255, s86, 58
	v_readlane_b32 s98, v254, 40
	s_nop 3
	s_cmp_lg_u32 s98, 0
	s_cbranch_scc1 .Lwo_sched_done
	s_mov_b32 s39, s82
	s_cmp_lt_u32 s82, 16
	s_cbranch_scc1 .Lwo_sched_lo
	s_sub_u32 s82, s82, 16
	s_movk_i32 s86, 0xf0
	s_movk_i32 s7, 0x100
	s_branch .Lwo_sched_set
.Lwo_sched_lo:
	s_add_u32 s82, s82, 0x100
	s_mov_b32 s86, 0x10000
	s_movk_i32 s7, 0x110
.Lwo_sched_set:
	v_writelane_b32 v255, s7, 8
	s_and_b32 s10, s82, 7
	s_mul_i32 s10, s10, 34
	s_lshr_b32 s11, s82, 3
	s_add_u32 s10, s10, s11
	s_lshr_b32 s11, s10, 4
	s_lshl_b32 s11, s11, 2
	s_and_b32 s12, s10, 3
	s_add_u32 s11, s11, s12
	s_bfe_u32 s12, s10, 0x20002
	v_writelane_b32 v255, s11, 12
	v_writelane_b32 v255, s12, 13
	s_lshl_b32 s34, s12, 19
	v_writelane_b32 v255, s34, 15
	s_mov_b32 s34, 0
	s_nop 0
	v_writelane_b32 v255, s34, 16
	v_readlane_b32 s98, v255, 30
	s_nop 3
	s_cmp_lg_u32 s98, 0
	s_cselect_b32 s38, 0x200, 0
	s_add_u32 s38, s38, 0x8000
	s_add_u32 s98, s88, s38
	s_addc_u32 s99, s89, 0
	s_lshl_b32 s11, s11, 2
	v_mov_b32_e32 v0, s11

	s_mov_b32 s7, 0
.Lwo_wait_a:
	global_load_dword v1, v0, s[98:99] sc1
	s_waitcnt vmcnt(0)
	v_readfirstlane_b32 s10, v1
	s_add_u32 s7, s7, 1
	s_cmp_ge_u32 s10, 4
	s_cbranch_scc1 .Lwo_wait_a_done
	s_sleep 2
	s_cmp_lt_u32 s7, 0x4000
	s_cbranch_scc1 .Lwo_wait_a
.Lwo_wait_a_done:

	s_sub_u32 s10, s39, 16
	s_cmp_lt_u32 s10, 16
	s_cbranch_scc0 .Lwo_wait_done
	s_add_u32 s10, s39, 224
	s_and_b32 s11, s10, 7
	s_mul_i32 s11, s11, 34
	s_lshr_b32 s10, s10, 3
	s_add_u32 s10, s11, s10
	s_lshr_b32 s11, s10, 4
	s_lshl_b32 s11, s11, 2
	s_and_b32 s10, s10, 3
	s_add_u32 s11, s11, s10
	s_lshl_b32 s11, s11, 2
	v_mov_b32_e32 v0, s11

	s_mov_b32 s7, 0

.Lwo_wait_b_done:

.Lwo_wait_done:
	buffer_inv sc1
	s_waitcnt vmcnt(0)

.LBB0_1567:
	v_readlane_b32 s98, v255, 52
	v_readlane_b32 s99, v255, 53
	s_nop 1
	v_writelane_b32 v255, s98, 12
	v_writelane_b32 v255, s99, 13
	v_readlane_b32 s98, v255, 54
	v_readlane_b32 s99, v255, 55
	s_nop 1
	v_writelane_b32 v255, s98, 15
	v_writelane_b32 v255, s99, 16
	v_readlane_b32 s98, v255, 56
	s_nop 1
	v_writelane_b32 v255, s98, 8
	v_readlane_b32 s82, v255, 57
	v_readlane_b32 s86, v255, 58
	s_nop 1
	s_waitcnt vmcnt(0)
	s_waitcnt lgkmcnt(0)
	s_barrier
	v_readlane_b32 s98, v255, 30
	v_readlane_b32 s99, v255, 31
	s_nop 3
	s_cmp_lg_u64 s[98:99], 0
	s_cbranch_scc1 .Lwo_gsync_do
	v_readlane_b32 s30, v254, 42
	v_readlane_b32 s31, v254, 43
	v_readlane_b32 s42, v254, 44
	v_readlane_b32 s43, v254, 45
	s_mov_b32 s38, 1
	s_mov_b64 s[6:7], 0
	s_branch .LBB0_268
